# v30 plus strategy 7.4 mirrored: static s_setprio 1 for waves 0-3 during the attention phase
# speedup vs baseline: 1.0044x; 1.0023x over previous
.LBB0_776:
	s_cmp_lt_i32 s74, 6
	v_writelane_b32 v254, s72, 40
	s_cselect_b64 s[4:5], -1, 0
	s_and_b64 s[0:1], s[4:5], s[2:3]
	v_writelane_b32 v254, s73, 41
	v_writelane_b32 v254, s74, 42
	v_writelane_b32 v254, s75, 43
	v_writelane_b32 v254, s76, 44
	s_andn2_b64 vcc, exec, s[0:1]
	s_nop 0
	v_writelane_b32 v254, s77, 45
	s_cbranch_vccnz .LBB0_2355
	s_add_u32 s36, s72, 0xe000000
	s_addc_u32 s37, s73, 0
	v_writelane_b32 v254, s4, 46
	s_add_u32 s0, s72, 0x300000
	s_addc_u32 s1, s73, 0
	v_writelane_b32 v254, s5, 47
	v_writelane_b32 v254, s0, 48
	s_mov_b32 s71, 0
	s_mov_b32 s79, s71
	v_writelane_b32 v254, s1, 49
	s_add_u32 s0, s72, 0x700000
	s_addc_u32 s1, s73, 0
	v_writelane_b32 v254, s0, 50
	s_mov_b64 s[86:87], s[74:75]
	s_mov_b64 s[84:85], s[72:73]
	v_writelane_b32 v254, s1, 51
	s_add_u32 s0, s72, 0x6000000
	s_addc_u32 s1, s73, 0
	v_writelane_b32 v254, s0, 52
	s_mov_b32 s2, s78
	v_and_b32_e32 v214, 0x3ff, v0
	v_writelane_b32 v254, s1, 53
	s_lshl_b64 s[0:1], s[78:79], 20
	s_add_u32 s0, s72, s0
	s_addc_u32 s1, s73, s1
	s_add_u32 s86, s0, 0x2c000000
	s_addc_u32 s87, s1, 0
	s_add_u32 s0, s76, 0xb0
	s_addc_u32 s1, s77, 0
	v_writelane_b32 v254, s0, 54
	v_cmp_eq_u32_e64 s[10:11], 0, v214
	v_mov_b32_e32 v149, 0
	v_writelane_b32 v254, s1, 55
	s_add_u32 s0, s84, 0x900000
	v_writelane_b32 v254, s0, 56
	s_addc_u32 s0, s85, 0
	v_writelane_b32 v254, s0, 57
	s_mov_b32 s0, 0x20000
	s_addk_i32 s0, 0x100
	v_writelane_b32 v254, s0, 58
	v_mov_b32_e32 v1, s0
	s_mov_b32 s0, 0x16000
	s_addk_i32 s0, 0x100
	v_writelane_b32 v254, s0, 60
	s_mov_b32 s0, s2
	v_writelane_b32 v254, s0, 61
	v_mbcnt_lo_u32_b32 v2, -1, 0
	s_movk_i32 s38, 0x100
	v_writelane_b32 v254, s1, 62
	v_writelane_b32 v254, s36, 63
	s_movk_i32 s33, 0x1e00
	s_brev_b32 s75, 1
	v_writelane_b32 v255, s37, 0
	v_writelane_b32 v255, s10, 1
	s_mov_b32 s39, 0xff800000
	s_mov_b64 s[90:91], 0x900
	s_mov_b64 s[92:93], 0x940
	s_mov_b64 s[94:95], 0xb80
	s_mov_b64 s[96:97], 0x1200
	s_mov_b64 s[68:69], 0x1240
	s_mov_b64 s[78:79], 0x1b00
	s_mov_b64 s[54:55], 0x1b40
	v_mov_b32_e32 v147, 0x1e00
	v_bfrev_b32_e32 v172, 1
	v_mov_b32_e32 v173, 0xfa
	v_mov_b32_e32 v216, 0xff800000
	v_mbcnt_hi_u32_b32 v217, -1, v2
	v_mov_b32_e32 v215, 0x200
	v_mov_b32_e32 v229, 0x100
	s_mov_b32 s0, s2
	s_mov_b32 s2, 0
	v_writelane_b32 v255, s11, 2
	v_readfirstlane_b32 s98, v0
	s_nop 3
	s_and_b32 s98, s98, 0x3ff
	s_lshr_b32 s98, s98, 6
	s_cmp_ge_u32 s98, 4
	s_cbranch_scc1 .Lprio_done_a
	s_setprio 1

.LBB0_3035:
	s_cmp_lt_i32 s74, 14
	s_cselect_b64 s[4:5], -1, 0
	s_and_b64 s[0:1], s[4:5], s[2:3]
	s_andn2_b64 vcc, exec, s[0:1]
	s_cbranch_vccnz .LBB0_4614
	s_add_u32 s2, s72, 0xe000000
	s_addc_u32 s3, s73, 0
	v_writelane_b32 v254, s4, 46
	s_add_u32 s0, s72, 0x300000
	s_addc_u32 s1, s73, 0
	v_writelane_b32 v254, s5, 47
	v_writelane_b32 v254, s0, 48
	s_mov_b32 s37, 0
	s_mov_b32 s79, s37
	v_writelane_b32 v254, s1, 49
	s_add_u32 s0, s72, 0x700000
	s_addc_u32 s1, s73, 0
	v_writelane_b32 v255, s0, 1
	s_mov_b32 s4, s78
	v_and_b32_e32 v214, 0x3ff, v0
	v_writelane_b32 v255, s1, 2
	s_add_u32 s0, s72, 0x6000000
	s_addc_u32 s1, s73, 0
	v_writelane_b32 v255, s0, 25
	v_cmp_eq_u32_e64 s[10:11], 0, v214
	v_mov_b32_e32 v149, 0
	v_writelane_b32 v255, s1, 26
	s_lshl_b64 s[0:1], s[78:79], 20
	s_add_u32 s0, s72, s0
	s_addc_u32 s1, s73, s1
	s_waitcnt lgkmcnt(0)
	s_add_u32 s62, s0, 0x2c000000
	s_addc_u32 s63, s1, 0
	s_add_u32 s0, s76, 0xb0
	s_addc_u32 s1, s77, 0
	v_writelane_b32 v255, s0, 5
	v_mbcnt_lo_u32_b32 v2, -1, 0
	s_movk_i32 s38, 0x100
	v_writelane_b32 v255, s1, 6
	s_add_u32 s0, s72, 0x900000
	v_writelane_b32 v254, s0, 57
	s_addc_u32 s0, s73, 0
	v_writelane_b32 v254, s0, 56
	s_mov_b32 s0, 0x20000
	s_addk_i32 s0, 0x100
	v_writelane_b32 v255, s0, 18
	v_mov_b32_e32 v1, s0
	s_mov_b32 s0, 0x16000
	s_addk_i32 s0, 0x100
	v_writelane_b32 v254, s0, 60
	s_mov_b32 s0, s4
	v_writelane_b32 v254, s0, 61
	v_writelane_b32 v255, s2, 23
	s_movk_i32 s33, 0x1e00
	v_writelane_b32 v254, s1, 62
	v_writelane_b32 v254, s10, 58
	s_brev_b32 s57, 1
	s_mov_b32 s39, 0xff800000
	s_mov_b64 s[70:71], 0x900
	s_mov_b64 s[72:73], 0x940
	s_mov_b64 s[74:75], 0xb80
	s_mov_b64 s[76:77], 0x1200
	s_mov_b64 s[78:79], 0x1240
	s_mov_b64 s[84:85], 0x1b00
	s_mov_b64 s[86:87], 0x1b40
	v_mov_b32_e32 v147, 0x1e00
	v_bfrev_b32_e32 v172, 1
	v_mov_b32_e32 v173, 0xfa
	v_mov_b32_e32 v216, 0xff800000
	v_mbcnt_hi_u32_b32 v217, -1, v2
	v_mov_b32_e32 v215, 0x200
	v_mov_b32_e32 v229, 0x100
	s_mov_b32 s0, s4
	s_mov_b32 s4, 0
	v_writelane_b32 v255, s3, 24
	v_writelane_b32 v254, s11, 59
	v_readfirstlane_b32 s98, v0
	s_nop 3
	s_and_b32 s98, s98, 0x3ff
	s_lshr_b32 s98, s98, 6
	s_cmp_ge_u32 s98, 4
	s_cbranch_scc1 .Lprio_done_b
	s_setprio 1
